# two wait states ahead of each LDS instruction of the recurrence loop
# baseline (speedup 1.0000x reference)
.LBB0_682:
	s_bitcmp1_b32 s30, 0
	s_cselect_b32 s6, 0xe000, 0
	s_add_i32 s6, s6, 0
	v_add_u32_e32 v90, s6, v58
	v_sub_u32_e32 v88, v90, v61
	v_add_u32_e32 v89, s6, v86
	ds_read_b128 v[4:7], v90 offset:0x4000
	ds_read_b128 v[8:11], v90 offset:0x0
	ds_read2st64_b32 v[108:109], v89 offset0:192 offset1:193
	ds_read2st64_b64 v[100:103], v88 offset0:64 offset1:65
	ds_read_b128 v[112:115], v90 offset:0x4200
	ds_read_b128 v[96:99], v90 offset:0x200
	ds_read_b128 v[120:123], v90 offset:0x4400
	ds_read_b128 v[124:127], v90 offset:0x400
	v_mov_b32_e32 v93, v91
	s_waitcnt lgkmcnt(5)
	v_pk_mul_f32 v[0:1], v[52:53], v[4:5] op_sel_hi:[0,1]
	v_pk_fma_f32 v[0:1], v[52:53], v[6:7], v[0:1] op_sel:[1,0,0]
	v_pk_mul_f32 v[10:11], v[108:109], v[10:11] op_sel_hi:[0,1]
	v_pk_fma_f32 v[54:55], v[52:53], v[8:9], v[10:11]
	v_add_f32_dpp v0, v0, v0 quad_perm:[1,0,3,2] row_mask:0xf bank_mask:0xf bound_ctrl:1
	v_add_f32_dpp v1, v1, v1 quad_perm:[1,0,3,2] row_mask:0xf bank_mask:0xf bound_ctrl:1
	s_nop 1
	ds_read_b128 v[4:7], v90 offset:0x4600
	v_add_f32_dpp v0, v0, v0 quad_perm:[2,3,0,1] row_mask:0xf bank_mask:0xf bound_ctrl:1
	s_nop 1
	ds_read_b128 v[8:11], v90 offset:0x600
	v_add_f32_dpp v0, v0, v0 row_half_mirror row_mask:0xf bank_mask:0xf bound_ctrl:1
	s_nop 1
	ds_read2st64_b32 v[110:111], v89 offset0:194 offset1:195
	ds_read2st64_b64 v[104:107], v88 offset0:66 offset1:67
	v_add_f32_dpp v2, v0, v0 row_mirror row_mask:0xf bank_mask:0xf bound_ctrl:1
	v_add_f32_dpp v0, v0, v0 row_mirror row_mask:0xf bank_mask:0xf bound_ctrl:1
	s_nop 0
	s_waitcnt lgkmcnt(6)
	v_permlane16_swap_b32_e32 v0, v2
	v_add_f32_e32 v0, v0, v2
	v_pk_fma_f32 v[52:53], v[100:101], v[0:1], v[54:55] op_sel_hi:[1,0,1]
	v_pk_mul_f32 v[118:119], v[52:53], v[112:113] op_sel_hi:[0,1]
	v_pk_fma_f32 v[118:119], v[52:53], v[114:115], v[118:119] op_sel:[1,0,0]
	v_pk_mul_f32 v[98:99], v[108:109], v[98:99] op_sel:[1,0]
	v_pk_fma_f32 v[54:55], v[52:53], v[96:97], v[98:99]
	v_add_f32_dpp v118, v118, v118 quad_perm:[1,0,3,2] row_mask:0xf bank_mask:0xf bound_ctrl:1
	v_add_f32_dpp v119, v119, v119 quad_perm:[1,0,3,2] row_mask:0xf bank_mask:0xf bound_ctrl:1
	s_nop 1
	ds_read_b128 v[112:115], v90 offset:0x4800
	v_add_f32_dpp v118, v118, v118 quad_perm:[2,3,0,1] row_mask:0xf bank_mask:0xf bound_ctrl:1
	s_nop 1
	ds_read_b128 v[96:99], v90 offset:0x800
	v_add_f32_dpp v118, v118, v118 row_half_mirror row_mask:0xf bank_mask:0xf bound_ctrl:1
	s_nop 1
	ds_write2_b32 v93, v1, v119 offset0:0 offset1:36
	v_add_f32_dpp v2, v118, v118 row_mirror row_mask:0xf bank_mask:0xf bound_ctrl:1
	v_add_f32_dpp v118, v118, v118 row_mirror row_mask:0xf bank_mask:0xf bound_ctrl:1
	s_nop 0
	s_waitcnt lgkmcnt(4)
	v_permlane16_swap_b32_e32 v118, v2
	v_add_f32_e32 v118, v118, v2
	v_pk_fma_f32 v[52:53], v[102:103], v[118:119], v[54:55] op_sel_hi:[1,0,1]
	v_pk_mul_f32 v[0:1], v[52:53], v[120:121] op_sel_hi:[0,1]
	v_pk_fma_f32 v[0:1], v[52:53], v[122:123], v[0:1] op_sel:[1,0,0]
	v_pk_mul_f32 v[126:127], v[110:111], v[126:127] op_sel_hi:[0,1]
	v_pk_fma_f32 v[54:55], v[52:53], v[124:125], v[126:127]
	v_add_f32_dpp v0, v0, v0 quad_perm:[1,0,3,2] row_mask:0xf bank_mask:0xf bound_ctrl:1
	v_add_f32_dpp v1, v1, v1 quad_perm:[1,0,3,2] row_mask:0xf bank_mask:0xf bound_ctrl:1
	s_nop 1
	ds_read_b128 v[120:123], v90 offset:0x4a00
	v_add_f32_dpp v0, v0, v0 quad_perm:[2,3,0,1] row_mask:0xf bank_mask:0xf bound_ctrl:1
	s_nop 1
	ds_read_b128 v[124:127], v90 offset:0xa00
	v_add_f32_dpp v0, v0, v0 row_half_mirror row_mask:0xf bank_mask:0xf bound_ctrl:1
	s_nop 1
	ds_read2st64_b32 v[108:109], v89 offset0:196 offset1:197
	ds_read2st64_b64 v[100:103], v88 offset0:68 offset1:69
	v_add_f32_dpp v2, v0, v0 row_mirror row_mask:0xf bank_mask:0xf bound_ctrl:1
	v_add_f32_dpp v0, v0, v0 row_mirror row_mask:0xf bank_mask:0xf bound_ctrl:1
	s_nop 0
	s_waitcnt lgkmcnt(7)
	v_permlane16_swap_b32_e32 v0, v2
	v_add_f32_e32 v0, v0, v2
	v_pk_fma_f32 v[52:53], v[104:105], v[0:1], v[54:55] op_sel_hi:[1,0,1]
	v_pk_mul_f32 v[118:119], v[52:53], v[4:5] op_sel_hi:[0,1]
	v_pk_fma_f32 v[118:119], v[52:53], v[6:7], v[118:119] op_sel:[1,0,0]
	v_pk_mul_f32 v[10:11], v[110:111], v[10:11] op_sel:[1,0]
	v_pk_fma_f32 v[54:55], v[52:53], v[8:9], v[10:11]
	v_add_f32_dpp v118, v118, v118 quad_perm:[1,0,3,2] row_mask:0xf bank_mask:0xf bound_ctrl:1
	v_add_f32_dpp v119, v119, v119 quad_perm:[1,0,3,2] row_mask:0xf bank_mask:0xf bound_ctrl:1
	s_nop 1
	ds_read_b128 v[4:7], v90 offset:0x4c00
	v_add_f32_dpp v118, v118, v118 quad_perm:[2,3,0,1] row_mask:0xf bank_mask:0xf bound_ctrl:1
	s_nop 1
	ds_read_b128 v[8:11], v90 offset:0xc00
	v_add_f32_dpp v118, v118, v118 row_half_mirror row_mask:0xf bank_mask:0xf bound_ctrl:1
	s_nop 1
	ds_write2_b32 v93, v1, v119 offset0:72 offset1:108
	v_add_f32_dpp v2, v118, v118 row_mirror row_mask:0xf bank_mask:0xf bound_ctrl:1
	v_add_f32_dpp v118, v118, v118 row_mirror row_mask:0xf bank_mask:0xf bound_ctrl:1
	s_nop 0
	s_waitcnt lgkmcnt(4)
	v_permlane16_swap_b32_e32 v118, v2
	v_add_f32_e32 v118, v118, v2
	v_pk_fma_f32 v[52:53], v[106:107], v[118:119], v[54:55] op_sel_hi:[1,0,1]
	v_pk_mul_f32 v[0:1], v[52:53], v[112:113] op_sel_hi:[0,1]
	v_pk_fma_f32 v[0:1], v[52:53], v[114:115], v[0:1] op_sel:[1,0,0]
	v_pk_mul_f32 v[98:99], v[108:109], v[98:99] op_sel_hi:[0,1]
	v_pk_fma_f32 v[54:55], v[52:53], v[96:97], v[98:99]
	v_add_f32_dpp v0, v0, v0 quad_perm:[1,0,3,2] row_mask:0xf bank_mask:0xf bound_ctrl:1
	v_add_f32_dpp v1, v1, v1 quad_perm:[1,0,3,2] row_mask:0xf bank_mask:0xf bound_ctrl:1
	s_nop 1
	ds_read_b128 v[112:115], v90 offset:0x4e00
	v_add_f32_dpp v0, v0, v0 quad_perm:[2,3,0,1] row_mask:0xf bank_mask:0xf bound_ctrl:1
	s_nop 1
	ds_read_b128 v[96:99], v90 offset:0xe00
	v_add_f32_dpp v0, v0, v0 row_half_mirror row_mask:0xf bank_mask:0xf bound_ctrl:1
	s_nop 1
	ds_read2st64_b32 v[110:111], v89 offset0:198 offset1:199
	ds_read2st64_b64 v[104:107], v88 offset0:70 offset1:71
	v_add_f32_dpp v2, v0, v0 row_mirror row_mask:0xf bank_mask:0xf bound_ctrl:1
	v_add_f32_dpp v0, v0, v0 row_mirror row_mask:0xf bank_mask:0xf bound_ctrl:1
	s_nop 0
	s_waitcnt lgkmcnt(7)
	v_permlane16_swap_b32_e32 v0, v2
	v_add_f32_e32 v0, v0, v2
	v_pk_fma_f32 v[52:53], v[100:101], v[0:1], v[54:55] op_sel_hi:[1,0,1]
	v_pk_mul_f32 v[118:119], v[52:53], v[120:121] op_sel_hi:[0,1]
	v_pk_fma_f32 v[118:119], v[52:53], v[122:123], v[118:119] op_sel:[1,0,0]
	v_pk_mul_f32 v[126:127], v[108:109], v[126:127] op_sel:[1,0]
	v_pk_fma_f32 v[54:55], v[52:53], v[124:125], v[126:127]
	v_add_f32_dpp v118, v118, v118 quad_perm:[1,0,3,2] row_mask:0xf bank_mask:0xf bound_ctrl:1
	v_add_f32_dpp v119, v119, v119 quad_perm:[1,0,3,2] row_mask:0xf bank_mask:0xf bound_ctrl:1
	s_nop 1
	ds_read_b128 v[120:123], v90 offset:0x5000
	v_add_f32_dpp v118, v118, v118 quad_perm:[2,3,0,1] row_mask:0xf bank_mask:0xf bound_ctrl:1
	s_nop 1
	ds_read_b128 v[124:127], v90 offset:0x1000
	v_add_f32_dpp v118, v118, v118 row_half_mirror row_mask:0xf bank_mask:0xf bound_ctrl:1
	s_nop 1
	ds_write2_b32 v93, v1, v119 offset0:144 offset1:180
	v_add_f32_dpp v2, v118, v118 row_mirror row_mask:0xf bank_mask:0xf bound_ctrl:1
	v_add_f32_dpp v118, v118, v118 row_mirror row_mask:0xf bank_mask:0xf bound_ctrl:1
	s_nop 0
	s_waitcnt lgkmcnt(4)
	v_permlane16_swap_b32_e32 v118, v2
	v_add_f32_e32 v118, v118, v2
	v_pk_fma_f32 v[52:53], v[102:103], v[118:119], v[54:55] op_sel_hi:[1,0,1]
	v_pk_mul_f32 v[0:1], v[52:53], v[4:5] op_sel_hi:[0,1]
	v_pk_fma_f32 v[0:1], v[52:53], v[6:7], v[0:1] op_sel:[1,0,0]
	v_pk_mul_f32 v[10:11], v[110:111], v[10:11] op_sel_hi:[0,1]
	v_pk_fma_f32 v[54:55], v[52:53], v[8:9], v[10:11]
	v_add_f32_dpp v0, v0, v0 quad_perm:[1,0,3,2] row_mask:0xf bank_mask:0xf bound_ctrl:1
	v_add_f32_dpp v1, v1, v1 quad_perm:[1,0,3,2] row_mask:0xf bank_mask:0xf bound_ctrl:1
	s_nop 1
	ds_read_b128 v[4:7], v90 offset:0x5200
	v_add_f32_dpp v0, v0, v0 quad_perm:[2,3,0,1] row_mask:0xf bank_mask:0xf bound_ctrl:1
	s_nop 1
	ds_read_b128 v[8:11], v90 offset:0x1200
	v_add_f32_dpp v0, v0, v0 row_half_mirror row_mask:0xf bank_mask:0xf bound_ctrl:1
	s_nop 1
	ds_read2st64_b32 v[108:109], v89 offset0:200 offset1:201
	ds_read2st64_b64 v[100:103], v88 offset0:72 offset1:73
	v_add_f32_dpp v2, v0, v0 row_mirror row_mask:0xf bank_mask:0xf bound_ctrl:1
	v_add_f32_dpp v0, v0, v0 row_mirror row_mask:0xf bank_mask:0xf bound_ctrl:1
	s_nop 0
	s_waitcnt lgkmcnt(7)
	v_permlane16_swap_b32_e32 v0, v2
	v_add_f32_e32 v0, v0, v2
	v_pk_fma_f32 v[52:53], v[104:105], v[0:1], v[54:55] op_sel_hi:[1,0,1]
	v_pk_mul_f32 v[118:119], v[52:53], v[112:113] op_sel_hi:[0,1]
	v_pk_fma_f32 v[118:119], v[52:53], v[114:115], v[118:119] op_sel:[1,0,0]
	v_pk_mul_f32 v[98:99], v[110:111], v[98:99] op_sel:[1,0]
	v_pk_fma_f32 v[54:55], v[52:53], v[96:97], v[98:99]
	v_add_f32_dpp v118, v118, v118 quad_perm:[1,0,3,2] row_mask:0xf bank_mask:0xf bound_ctrl:1
	v_add_f32_dpp v119, v119, v119 quad_perm:[1,0,3,2] row_mask:0xf bank_mask:0xf bound_ctrl:1
	s_nop 1
	ds_read_b128 v[112:115], v90 offset:0x5400
	v_add_f32_dpp v118, v118, v118 quad_perm:[2,3,0,1] row_mask:0xf bank_mask:0xf bound_ctrl:1
	s_nop 1
	ds_read_b128 v[96:99], v90 offset:0x1400
	v_add_f32_dpp v118, v118, v118 row_half_mirror row_mask:0xf bank_mask:0xf bound_ctrl:1
	s_nop 1
	ds_write2_b32 v93, v1, v119 offset0:216 offset1:252
	v_add_f32_dpp v2, v118, v118 row_mirror row_mask:0xf bank_mask:0xf bound_ctrl:1
	v_add_f32_dpp v118, v118, v118 row_mirror row_mask:0xf bank_mask:0xf bound_ctrl:1
	s_nop 0
	s_waitcnt lgkmcnt(4)
	v_permlane16_swap_b32_e32 v118, v2
	v_add_f32_e32 v118, v118, v2
	v_pk_fma_f32 v[52:53], v[106:107], v[118:119], v[54:55] op_sel_hi:[1,0,1]
	v_pk_mul_f32 v[0:1], v[52:53], v[120:121] op_sel_hi:[0,1]
	v_pk_fma_f32 v[0:1], v[52:53], v[122:123], v[0:1] op_sel:[1,0,0]
	v_pk_mul_f32 v[126:127], v[108:109], v[126:127] op_sel_hi:[0,1]
	v_pk_fma_f32 v[54:55], v[52:53], v[124:125], v[126:127]
	v_add_f32_dpp v0, v0, v0 quad_perm:[1,0,3,2] row_mask:0xf bank_mask:0xf bound_ctrl:1
	v_add_f32_dpp v1, v1, v1 quad_perm:[1,0,3,2] row_mask:0xf bank_mask:0xf bound_ctrl:1
	s_nop 1
	ds_read_b128 v[120:123], v90 offset:0x5600
	v_add_f32_dpp v0, v0, v0 quad_perm:[2,3,0,1] row_mask:0xf bank_mask:0xf bound_ctrl:1
	s_nop 1
	ds_read_b128 v[124:127], v90 offset:0x1600
	v_add_f32_dpp v0, v0, v0 row_half_mirror row_mask:0xf bank_mask:0xf bound_ctrl:1
	s_nop 1
	ds_read2st64_b32 v[110:111], v89 offset0:202 offset1:203
	ds_read2st64_b64 v[104:107], v88 offset0:74 offset1:75
	v_add_f32_dpp v2, v0, v0 row_mirror row_mask:0xf bank_mask:0xf bound_ctrl:1
	v_add_f32_dpp v0, v0, v0 row_mirror row_mask:0xf bank_mask:0xf bound_ctrl:1
	v_add_u32_e32 v93, 0x480, v93
	s_waitcnt lgkmcnt(7)
	v_permlane16_swap_b32_e32 v0, v2
	v_add_f32_e32 v0, v0, v2
	v_pk_fma_f32 v[52:53], v[100:101], v[0:1], v[54:55] op_sel_hi:[1,0,1]
	v_pk_mul_f32 v[118:119], v[52:53], v[4:5] op_sel_hi:[0,1]
	v_pk_fma_f32 v[118:119], v[52:53], v[6:7], v[118:119] op_sel:[1,0,0]
	v_pk_mul_f32 v[10:11], v[108:109], v[10:11] op_sel:[1,0]
	v_pk_fma_f32 v[54:55], v[52:53], v[8:9], v[10:11]
	v_add_f32_dpp v118, v118, v118 quad_perm:[1,0,3,2] row_mask:0xf bank_mask:0xf bound_ctrl:1
	v_add_f32_dpp v119, v119, v119 quad_perm:[1,0,3,2] row_mask:0xf bank_mask:0xf bound_ctrl:1
	s_nop 1
	ds_read_b128 v[4:7], v90 offset:0x5800
	v_add_f32_dpp v118, v118, v118 quad_perm:[2,3,0,1] row_mask:0xf bank_mask:0xf bound_ctrl:1
	s_nop 1
	ds_read_b128 v[8:11], v90 offset:0x1800
	v_add_f32_dpp v118, v118, v118 row_half_mirror row_mask:0xf bank_mask:0xf bound_ctrl:1
	s_nop 1
	ds_write2_b32 v93, v1, v119 offset0:0 offset1:36
	v_add_f32_dpp v2, v118, v118 row_mirror row_mask:0xf bank_mask:0xf bound_ctrl:1
	v_add_f32_dpp v118, v118, v118 row_mirror row_mask:0xf bank_mask:0xf bound_ctrl:1
	s_nop 0
	s_waitcnt lgkmcnt(4)
	v_permlane16_swap_b32_e32 v118, v2
	v_add_f32_e32 v118, v118, v2
	v_pk_fma_f32 v[52:53], v[102:103], v[118:119], v[54:55] op_sel_hi:[1,0,1]
	v_pk_mul_f32 v[0:1], v[52:53], v[112:113] op_sel_hi:[0,1]
	v_pk_fma_f32 v[0:1], v[52:53], v[114:115], v[0:1] op_sel:[1,0,0]
	v_pk_mul_f32 v[98:99], v[110:111], v[98:99] op_sel_hi:[0,1]
	v_pk_fma_f32 v[54:55], v[52:53], v[96:97], v[98:99]
	v_add_f32_dpp v0, v0, v0 quad_perm:[1,0,3,2] row_mask:0xf bank_mask:0xf bound_ctrl:1
	v_add_f32_dpp v1, v1, v1 quad_perm:[1,0,3,2] row_mask:0xf bank_mask:0xf bound_ctrl:1
	s_nop 1
	ds_read_b128 v[112:115], v90 offset:0x5a00
	v_add_f32_dpp v0, v0, v0 quad_perm:[2,3,0,1] row_mask:0xf bank_mask:0xf bound_ctrl:1
	s_nop 1
	ds_read_b128 v[96:99], v90 offset:0x1a00
	v_add_f32_dpp v0, v0, v0 row_half_mirror row_mask:0xf bank_mask:0xf bound_ctrl:1
	s_nop 1
	ds_read2st64_b32 v[108:109], v89 offset0:204 offset1:205
	ds_read2st64_b64 v[100:103], v88 offset0:76 offset1:77
	v_add_f32_dpp v2, v0, v0 row_mirror row_mask:0xf bank_mask:0xf bound_ctrl:1
	v_add_f32_dpp v0, v0, v0 row_mirror row_mask:0xf bank_mask:0xf bound_ctrl:1
	s_nop 0
	s_waitcnt lgkmcnt(7)
	v_permlane16_swap_b32_e32 v0, v2
	v_add_f32_e32 v0, v0, v2
	v_pk_fma_f32 v[52:53], v[104:105], v[0:1], v[54:55] op_sel_hi:[1,0,1]
	v_pk_mul_f32 v[118:119], v[52:53], v[120:121] op_sel_hi:[0,1]
	v_pk_fma_f32 v[118:119], v[52:53], v[122:123], v[118:119] op_sel:[1,0,0]
	v_pk_mul_f32 v[126:127], v[110:111], v[126:127] op_sel:[1,0]
	v_pk_fma_f32 v[54:55], v[52:53], v[124:125], v[126:127]
	v_add_f32_dpp v118, v118, v118 quad_perm:[1,0,3,2] row_mask:0xf bank_mask:0xf bound_ctrl:1
	v_add_f32_dpp v119, v119, v119 quad_perm:[1,0,3,2] row_mask:0xf bank_mask:0xf bound_ctrl:1
	s_nop 1
	ds_read_b128 v[120:123], v90 offset:0x5c00
	v_add_f32_dpp v118, v118, v118 quad_perm:[2,3,0,1] row_mask:0xf bank_mask:0xf bound_ctrl:1
	s_nop 1
	ds_read_b128 v[124:127], v90 offset:0x1c00
	v_add_f32_dpp v118, v118, v118 row_half_mirror row_mask:0xf bank_mask:0xf bound_ctrl:1
	s_nop 1
	ds_write2_b32 v93, v1, v119 offset0:72 offset1:108
	v_add_f32_dpp v2, v118, v118 row_mirror row_mask:0xf bank_mask:0xf bound_ctrl:1
	v_add_f32_dpp v118, v118, v118 row_mirror row_mask:0xf bank_mask:0xf bound_ctrl:1
	s_nop 0
	s_waitcnt lgkmcnt(4)
	v_permlane16_swap_b32_e32 v118, v2
	v_add_f32_e32 v118, v118, v2
	v_pk_fma_f32 v[52:53], v[106:107], v[118:119], v[54:55] op_sel_hi:[1,0,1]
	v_pk_mul_f32 v[0:1], v[52:53], v[4:5] op_sel_hi:[0,1]
	v_pk_fma_f32 v[0:1], v[52:53], v[6:7], v[0:1] op_sel:[1,0,0]
	v_pk_mul_f32 v[10:11], v[108:109], v[10:11] op_sel_hi:[0,1]
	v_pk_fma_f32 v[54:55], v[52:53], v[8:9], v[10:11]
	v_add_f32_dpp v0, v0, v0 quad_perm:[1,0,3,2] row_mask:0xf bank_mask:0xf bound_ctrl:1
	v_add_f32_dpp v1, v1, v1 quad_perm:[1,0,3,2] row_mask:0xf bank_mask:0xf bound_ctrl:1
	s_nop 1
	ds_read_b128 v[4:7], v90 offset:0x5e00
	v_add_f32_dpp v0, v0, v0 quad_perm:[2,3,0,1] row_mask:0xf bank_mask:0xf bound_ctrl:1
	s_nop 1
	ds_read_b128 v[8:11], v90 offset:0x1e00
	v_add_f32_dpp v0, v0, v0 row_half_mirror row_mask:0xf bank_mask:0xf bound_ctrl:1
	s_nop 1
	ds_read2st64_b32 v[110:111], v89 offset0:206 offset1:207
	ds_read2st64_b64 v[104:107], v88 offset0:78 offset1:79
	v_add_f32_dpp v2, v0, v0 row_mirror row_mask:0xf bank_mask:0xf bound_ctrl:1
	v_add_f32_dpp v0, v0, v0 row_mirror row_mask:0xf bank_mask:0xf bound_ctrl:1
	s_nop 0
	s_waitcnt lgkmcnt(7)
	v_permlane16_swap_b32_e32 v0, v2
	v_add_f32_e32 v0, v0, v2
	v_pk_fma_f32 v[52:53], v[100:101], v[0:1], v[54:55] op_sel_hi:[1,0,1]
	v_pk_mul_f32 v[118:119], v[52:53], v[112:113] op_sel_hi:[0,1]
	v_pk_fma_f32 v[118:119], v[52:53], v[114:115], v[118:119] op_sel:[1,0,0]
	v_pk_mul_f32 v[98:99], v[108:109], v[98:99] op_sel:[1,0]
	v_pk_fma_f32 v[54:55], v[52:53], v[96:97], v[98:99]
	v_add_f32_dpp v118, v118, v118 quad_perm:[1,0,3,2] row_mask:0xf bank_mask:0xf bound_ctrl:1
	v_add_f32_dpp v119, v119, v119 quad_perm:[1,0,3,2] row_mask:0xf bank_mask:0xf bound_ctrl:1
	s_nop 1
	ds_read_b128 v[112:115], v90 offset:0x6000
	v_add_f32_dpp v118, v118, v118 quad_perm:[2,3,0,1] row_mask:0xf bank_mask:0xf bound_ctrl:1
	s_nop 1
	ds_read_b128 v[96:99], v90 offset:0x2000
	v_add_f32_dpp v118, v118, v118 row_half_mirror row_mask:0xf bank_mask:0xf bound_ctrl:1
	s_nop 1
	ds_write2_b32 v93, v1, v119 offset0:144 offset1:180
	v_add_f32_dpp v2, v118, v118 row_mirror row_mask:0xf bank_mask:0xf bound_ctrl:1
	v_add_f32_dpp v118, v118, v118 row_mirror row_mask:0xf bank_mask:0xf bound_ctrl:1
	s_nop 0
	s_waitcnt lgkmcnt(4)
	v_permlane16_swap_b32_e32 v118, v2
	v_add_f32_e32 v118, v118, v2
	v_pk_fma_f32 v[52:53], v[102:103], v[118:119], v[54:55] op_sel_hi:[1,0,1]
	v_pk_mul_f32 v[0:1], v[52:53], v[120:121] op_sel_hi:[0,1]
	v_pk_fma_f32 v[0:1], v[52:53], v[122:123], v[0:1] op_sel:[1,0,0]
	v_pk_mul_f32 v[126:127], v[110:111], v[126:127] op_sel_hi:[0,1]
	v_pk_fma_f32 v[54:55], v[52:53], v[124:125], v[126:127]
	v_add_f32_dpp v0, v0, v0 quad_perm:[1,0,3,2] row_mask:0xf bank_mask:0xf bound_ctrl:1
	v_add_f32_dpp v1, v1, v1 quad_perm:[1,0,3,2] row_mask:0xf bank_mask:0xf bound_ctrl:1
	s_nop 1
	ds_read_b128 v[120:123], v90 offset:0x6200
	v_add_f32_dpp v0, v0, v0 quad_perm:[2,3,0,1] row_mask:0xf bank_mask:0xf bound_ctrl:1
	s_nop 1
	ds_read_b128 v[124:127], v90 offset:0x2200
	v_add_f32_dpp v0, v0, v0 row_half_mirror row_mask:0xf bank_mask:0xf bound_ctrl:1
	s_nop 1
	ds_read2st64_b32 v[108:109], v89 offset0:208 offset1:209
	ds_read2st64_b64 v[100:103], v88 offset0:80 offset1:81
	v_add_f32_dpp v2, v0, v0 row_mirror row_mask:0xf bank_mask:0xf bound_ctrl:1
	v_add_f32_dpp v0, v0, v0 row_mirror row_mask:0xf bank_mask:0xf bound_ctrl:1
	s_nop 0
	s_waitcnt lgkmcnt(7)
	v_permlane16_swap_b32_e32 v0, v2
	v_add_f32_e32 v0, v0, v2
	v_pk_fma_f32 v[52:53], v[104:105], v[0:1], v[54:55] op_sel_hi:[1,0,1]
	v_pk_mul_f32 v[118:119], v[52:53], v[4:5] op_sel_hi:[0,1]
	v_pk_fma_f32 v[118:119], v[52:53], v[6:7], v[118:119] op_sel:[1,0,0]
	v_pk_mul_f32 v[10:11], v[110:111], v[10:11] op_sel:[1,0]
	v_pk_fma_f32 v[54:55], v[52:53], v[8:9], v[10:11]
	v_add_f32_dpp v118, v118, v118 quad_perm:[1,0,3,2] row_mask:0xf bank_mask:0xf bound_ctrl:1
	v_add_f32_dpp v119, v119, v119 quad_perm:[1,0,3,2] row_mask:0xf bank_mask:0xf bound_ctrl:1
	s_nop 1
	ds_read_b128 v[4:7], v90 offset:0x6400
	v_add_f32_dpp v118, v118, v118 quad_perm:[2,3,0,1] row_mask:0xf bank_mask:0xf bound_ctrl:1
	s_nop 1
	ds_read_b128 v[8:11], v90 offset:0x2400
	v_add_f32_dpp v118, v118, v118 row_half_mirror row_mask:0xf bank_mask:0xf bound_ctrl:1
	s_nop 1
	ds_write2_b32 v93, v1, v119 offset0:216 offset1:252
	v_add_f32_dpp v2, v118, v118 row_mirror row_mask:0xf bank_mask:0xf bound_ctrl:1
	v_add_f32_dpp v118, v118, v118 row_mirror row_mask:0xf bank_mask:0xf bound_ctrl:1
	s_nop 0
	s_waitcnt lgkmcnt(4)
	v_permlane16_swap_b32_e32 v118, v2
	v_add_f32_e32 v118, v118, v2
	v_pk_fma_f32 v[52:53], v[106:107], v[118:119], v[54:55] op_sel_hi:[1,0,1]
	s_cmp_eq_u32 s88, 0x800000
	s_cbranch_scc1 .LBB0_684
	v_pk_mul_f32 v[0:1], v[52:53], v[112:113] op_sel_hi:[0,1]
	v_pk_fma_f32 v[0:1], v[52:53], v[114:115], v[0:1] op_sel:[1,0,0]
	v_pk_mul_f32 v[98:99], v[108:109], v[98:99] op_sel_hi:[0,1]
	v_pk_fma_f32 v[54:55], v[52:53], v[96:97], v[98:99]
	v_add_f32_dpp v0, v0, v0 quad_perm:[1,0,3,2] row_mask:0xf bank_mask:0xf bound_ctrl:1
	v_add_f32_dpp v1, v1, v1 quad_perm:[1,0,3,2] row_mask:0xf bank_mask:0xf bound_ctrl:1
	s_nop 1
	ds_read_b128 v[112:115], v90 offset:0x6600
	v_add_f32_dpp v0, v0, v0 quad_perm:[2,3,0,1] row_mask:0xf bank_mask:0xf bound_ctrl:1
	s_nop 1
	ds_read_b128 v[96:99], v90 offset:0x2600
	v_add_f32_dpp v0, v0, v0 row_half_mirror row_mask:0xf bank_mask:0xf bound_ctrl:1
	s_nop 1
	ds_read2st64_b32 v[110:111], v89 offset0:210 offset1:211
	ds_read2st64_b64 v[104:107], v88 offset0:82 offset1:83
	v_add_f32_dpp v2, v0, v0 row_mirror row_mask:0xf bank_mask:0xf bound_ctrl:1
	v_add_f32_dpp v0, v0, v0 row_mirror row_mask:0xf bank_mask:0xf bound_ctrl:1
	v_add_u32_e32 v93, 0x480, v93
	s_waitcnt lgkmcnt(7)
	v_permlane16_swap_b32_e32 v0, v2
	v_add_f32_e32 v0, v0, v2
	v_pk_fma_f32 v[52:53], v[100:101], v[0:1], v[54:55] op_sel_hi:[1,0,1]
	v_pk_mul_f32 v[118:119], v[52:53], v[120:121] op_sel_hi:[0,1]
	v_pk_fma_f32 v[118:119], v[52:53], v[122:123], v[118:119] op_sel:[1,0,0]
	v_pk_mul_f32 v[126:127], v[108:109], v[126:127] op_sel:[1,0]
	v_pk_fma_f32 v[54:55], v[52:53], v[124:125], v[126:127]
	v_add_f32_dpp v118, v118, v118 quad_perm:[1,0,3,2] row_mask:0xf bank_mask:0xf bound_ctrl:1
	v_add_f32_dpp v119, v119, v119 quad_perm:[1,0,3,2] row_mask:0xf bank_mask:0xf bound_ctrl:1
	s_nop 1
	ds_read_b128 v[120:123], v90 offset:0x6800
	v_add_f32_dpp v118, v118, v118 quad_perm:[2,3,0,1] row_mask:0xf bank_mask:0xf bound_ctrl:1
	s_nop 1
	ds_read_b128 v[124:127], v90 offset:0x2800
	v_add_f32_dpp v118, v118, v118 row_half_mirror row_mask:0xf bank_mask:0xf bound_ctrl:1
	s_nop 1
	ds_write2_b32 v93, v1, v119 offset0:0 offset1:36
	v_add_f32_dpp v2, v118, v118 row_mirror row_mask:0xf bank_mask:0xf bound_ctrl:1
	v_add_f32_dpp v118, v118, v118 row_mirror row_mask:0xf bank_mask:0xf bound_ctrl:1
	s_nop 0
	s_waitcnt lgkmcnt(4)
	v_permlane16_swap_b32_e32 v118, v2
	v_add_f32_e32 v118, v118, v2
	v_pk_fma_f32 v[52:53], v[102:103], v[118:119], v[54:55] op_sel_hi:[1,0,1]
	v_pk_mul_f32 v[0:1], v[52:53], v[4:5] op_sel_hi:[0,1]
	v_pk_fma_f32 v[0:1], v[52:53], v[6:7], v[0:1] op_sel:[1,0,0]
	v_pk_mul_f32 v[10:11], v[110:111], v[10:11] op_sel_hi:[0,1]
	v_pk_fma_f32 v[54:55], v[52:53], v[8:9], v[10:11]
	v_add_f32_dpp v0, v0, v0 quad_perm:[1,0,3,2] row_mask:0xf bank_mask:0xf bound_ctrl:1
	v_add_f32_dpp v1, v1, v1 quad_perm:[1,0,3,2] row_mask:0xf bank_mask:0xf bound_ctrl:1
	s_nop 1
	ds_read_b128 v[4:7], v90 offset:0x6a00
	v_add_f32_dpp v0, v0, v0 quad_perm:[2,3,0,1] row_mask:0xf bank_mask:0xf bound_ctrl:1
	s_nop 1
	ds_read_b128 v[8:11], v90 offset:0x2a00
	v_add_f32_dpp v0, v0, v0 row_half_mirror row_mask:0xf bank_mask:0xf bound_ctrl:1
	s_nop 1
	ds_read2st64_b32 v[108:109], v89 offset0:212 offset1:213
	ds_read2st64_b64 v[100:103], v88 offset0:84 offset1:85
	v_add_f32_dpp v2, v0, v0 row_mirror row_mask:0xf bank_mask:0xf bound_ctrl:1
	v_add_f32_dpp v0, v0, v0 row_mirror row_mask:0xf bank_mask:0xf bound_ctrl:1
	s_nop 0
	s_waitcnt lgkmcnt(7)
	v_permlane16_swap_b32_e32 v0, v2
	v_add_f32_e32 v0, v0, v2
	v_pk_fma_f32 v[52:53], v[104:105], v[0:1], v[54:55] op_sel_hi:[1,0,1]
	v_pk_mul_f32 v[118:119], v[52:53], v[112:113] op_sel_hi:[0,1]
	v_pk_fma_f32 v[118:119], v[52:53], v[114:115], v[118:119] op_sel:[1,0,0]
	v_pk_mul_f32 v[98:99], v[110:111], v[98:99] op_sel:[1,0]
	v_pk_fma_f32 v[54:55], v[52:53], v[96:97], v[98:99]
	v_add_f32_dpp v118, v118, v118 quad_perm:[1,0,3,2] row_mask:0xf bank_mask:0xf bound_ctrl:1
	v_add_f32_dpp v119, v119, v119 quad_perm:[1,0,3,2] row_mask:0xf bank_mask:0xf bound_ctrl:1
	s_nop 1
	ds_read_b128 v[112:115], v90 offset:0x6c00
	v_add_f32_dpp v118, v118, v118 quad_perm:[2,3,0,1] row_mask:0xf bank_mask:0xf bound_ctrl:1
	s_nop 1
	ds_read_b128 v[96:99], v90 offset:0x2c00
	v_add_f32_dpp v118, v118, v118 row_half_mirror row_mask:0xf bank_mask:0xf bound_ctrl:1
	s_nop 1
	ds_write2_b32 v93, v1, v119 offset0:72 offset1:108
	v_add_f32_dpp v2, v118, v118 row_mirror row_mask:0xf bank_mask:0xf bound_ctrl:1
	v_add_f32_dpp v118, v118, v118 row_mirror row_mask:0xf bank_mask:0xf bound_ctrl:1
	s_nop 0
	s_waitcnt lgkmcnt(4)
	v_permlane16_swap_b32_e32 v118, v2
	v_add_f32_e32 v118, v118, v2
	v_pk_fma_f32 v[52:53], v[106:107], v[118:119], v[54:55] op_sel_hi:[1,0,1]
	v_pk_mul_f32 v[0:1], v[52:53], v[120:121] op_sel_hi:[0,1]
	v_pk_fma_f32 v[0:1], v[52:53], v[122:123], v[0:1] op_sel:[1,0,0]
	v_pk_mul_f32 v[126:127], v[108:109], v[126:127] op_sel_hi:[0,1]
	v_pk_fma_f32 v[54:55], v[52:53], v[124:125], v[126:127]
	v_add_f32_dpp v0, v0, v0 quad_perm:[1,0,3,2] row_mask:0xf bank_mask:0xf bound_ctrl:1
	v_add_f32_dpp v1, v1, v1 quad_perm:[1,0,3,2] row_mask:0xf bank_mask:0xf bound_ctrl:1
	s_nop 1
	ds_read_b128 v[120:123], v90 offset:0x6e00
	v_add_f32_dpp v0, v0, v0 quad_perm:[2,3,0,1] row_mask:0xf bank_mask:0xf bound_ctrl:1
	s_nop 1
	ds_read_b128 v[124:127], v90 offset:0x2e00
	v_add_f32_dpp v0, v0, v0 row_half_mirror row_mask:0xf bank_mask:0xf bound_ctrl:1
	s_nop 1
	ds_read2st64_b32 v[110:111], v89 offset0:214 offset1:215
	ds_read2st64_b64 v[104:107], v88 offset0:86 offset1:87
	v_add_f32_dpp v2, v0, v0 row_mirror row_mask:0xf bank_mask:0xf bound_ctrl:1
	v_add_f32_dpp v0, v0, v0 row_mirror row_mask:0xf bank_mask:0xf bound_ctrl:1
	s_nop 0
	s_waitcnt lgkmcnt(7)
	v_permlane16_swap_b32_e32 v0, v2
	v_add_f32_e32 v0, v0, v2
	v_pk_fma_f32 v[52:53], v[100:101], v[0:1], v[54:55] op_sel_hi:[1,0,1]
	v_pk_mul_f32 v[118:119], v[52:53], v[4:5] op_sel_hi:[0,1]
	v_pk_fma_f32 v[118:119], v[52:53], v[6:7], v[118:119] op_sel:[1,0,0]
	v_pk_mul_f32 v[10:11], v[108:109], v[10:11] op_sel:[1,0]
	v_pk_fma_f32 v[54:55], v[52:53], v[8:9], v[10:11]
	v_add_f32_dpp v118, v118, v118 quad_perm:[1,0,3,2] row_mask:0xf bank_mask:0xf bound_ctrl:1
	v_add_f32_dpp v119, v119, v119 quad_perm:[1,0,3,2] row_mask:0xf bank_mask:0xf bound_ctrl:1
	s_nop 1
	ds_read_b128 v[4:7], v90 offset:0x7000
	v_add_f32_dpp v118, v118, v118 quad_perm:[2,3,0,1] row_mask:0xf bank_mask:0xf bound_ctrl:1
	s_nop 1
	ds_read_b128 v[8:11], v90 offset:0x3000
	v_add_f32_dpp v118, v118, v118 row_half_mirror row_mask:0xf bank_mask:0xf bound_ctrl:1
	s_nop 1
	ds_write2_b32 v93, v1, v119 offset0:144 offset1:180
	v_add_f32_dpp v2, v118, v118 row_mirror row_mask:0xf bank_mask:0xf bound_ctrl:1
	v_add_f32_dpp v118, v118, v118 row_mirror row_mask:0xf bank_mask:0xf bound_ctrl:1
	s_nop 0
	s_waitcnt lgkmcnt(4)
	v_permlane16_swap_b32_e32 v118, v2
	v_add_f32_e32 v118, v118, v2
	v_pk_fma_f32 v[52:53], v[102:103], v[118:119], v[54:55] op_sel_hi:[1,0,1]
	v_pk_mul_f32 v[0:1], v[52:53], v[112:113] op_sel_hi:[0,1]
	v_pk_fma_f32 v[0:1], v[52:53], v[114:115], v[0:1] op_sel:[1,0,0]
	v_pk_mul_f32 v[98:99], v[110:111], v[98:99] op_sel_hi:[0,1]
	v_pk_fma_f32 v[54:55], v[52:53], v[96:97], v[98:99]
	v_add_f32_dpp v0, v0, v0 quad_perm:[1,0,3,2] row_mask:0xf bank_mask:0xf bound_ctrl:1
	v_add_f32_dpp v1, v1, v1 quad_perm:[1,0,3,2] row_mask:0xf bank_mask:0xf bound_ctrl:1
	s_nop 1
	ds_read_b128 v[112:115], v90 offset:0x7200
	v_add_f32_dpp v0, v0, v0 quad_perm:[2,3,0,1] row_mask:0xf bank_mask:0xf bound_ctrl:1
	s_nop 1
	ds_read_b128 v[96:99], v90 offset:0x3200
	v_add_f32_dpp v0, v0, v0 row_half_mirror row_mask:0xf bank_mask:0xf bound_ctrl:1
	s_nop 1
	ds_read2st64_b32 v[108:109], v89 offset0:216 offset1:217
	ds_read2st64_b64 v[100:103], v88 offset0:88 offset1:89
	v_add_f32_dpp v2, v0, v0 row_mirror row_mask:0xf bank_mask:0xf bound_ctrl:1
	v_add_f32_dpp v0, v0, v0 row_mirror row_mask:0xf bank_mask:0xf bound_ctrl:1
	s_nop 0
	s_waitcnt lgkmcnt(7)
	v_permlane16_swap_b32_e32 v0, v2
	v_add_f32_e32 v0, v0, v2
	v_pk_fma_f32 v[52:53], v[104:105], v[0:1], v[54:55] op_sel_hi:[1,0,1]
	v_pk_mul_f32 v[118:119], v[52:53], v[120:121] op_sel_hi:[0,1]
	v_pk_fma_f32 v[118:119], v[52:53], v[122:123], v[118:119] op_sel:[1,0,0]
	v_pk_mul_f32 v[126:127], v[110:111], v[126:127] op_sel:[1,0]
	v_pk_fma_f32 v[54:55], v[52:53], v[124:125], v[126:127]
	v_add_f32_dpp v118, v118, v118 quad_perm:[1,0,3,2] row_mask:0xf bank_mask:0xf bound_ctrl:1
	v_add_f32_dpp v119, v119, v119 quad_perm:[1,0,3,2] row_mask:0xf bank_mask:0xf bound_ctrl:1
	s_nop 1
	ds_read_b128 v[120:123], v90 offset:0x7400
	v_add_f32_dpp v118, v118, v118 quad_perm:[2,3,0,1] row_mask:0xf bank_mask:0xf bound_ctrl:1
	s_nop 1
	ds_read_b128 v[124:127], v90 offset:0x3400
	v_add_f32_dpp v118, v118, v118 row_half_mirror row_mask:0xf bank_mask:0xf bound_ctrl:1
	s_nop 1
	ds_write2_b32 v93, v1, v119 offset0:216 offset1:252
	v_add_f32_dpp v2, v118, v118 row_mirror row_mask:0xf bank_mask:0xf bound_ctrl:1
	v_add_f32_dpp v118, v118, v118 row_mirror row_mask:0xf bank_mask:0xf bound_ctrl:1
	s_nop 0
	s_waitcnt lgkmcnt(4)
	v_permlane16_swap_b32_e32 v118, v2
	v_add_f32_e32 v118, v118, v2
	v_pk_fma_f32 v[52:53], v[106:107], v[118:119], v[54:55] op_sel_hi:[1,0,1]
	v_pk_mul_f32 v[0:1], v[52:53], v[4:5] op_sel_hi:[0,1]
	v_pk_fma_f32 v[0:1], v[52:53], v[6:7], v[0:1] op_sel:[1,0,0]
	v_pk_mul_f32 v[10:11], v[108:109], v[10:11] op_sel_hi:[0,1]
	v_pk_fma_f32 v[54:55], v[52:53], v[8:9], v[10:11]
	v_add_f32_dpp v0, v0, v0 quad_perm:[1,0,3,2] row_mask:0xf bank_mask:0xf bound_ctrl:1
	v_add_f32_dpp v1, v1, v1 quad_perm:[1,0,3,2] row_mask:0xf bank_mask:0xf bound_ctrl:1
	s_nop 1
	ds_read_b128 v[4:7], v90 offset:0x7600
	v_add_f32_dpp v0, v0, v0 quad_perm:[2,3,0,1] row_mask:0xf bank_mask:0xf bound_ctrl:1
	s_nop 1
	ds_read_b128 v[8:11], v90 offset:0x3600
	v_add_f32_dpp v0, v0, v0 row_half_mirror row_mask:0xf bank_mask:0xf bound_ctrl:1
	s_nop 1
	ds_read2st64_b32 v[110:111], v89 offset0:218 offset1:219
	ds_read2st64_b64 v[104:107], v88 offset0:90 offset1:91
	v_add_f32_dpp v2, v0, v0 row_mirror row_mask:0xf bank_mask:0xf bound_ctrl:1
	v_add_f32_dpp v0, v0, v0 row_mirror row_mask:0xf bank_mask:0xf bound_ctrl:1
	v_add_u32_e32 v93, 0x480, v93
	s_waitcnt lgkmcnt(7)
	v_permlane16_swap_b32_e32 v0, v2
	v_add_f32_e32 v0, v0, v2
	v_pk_fma_f32 v[52:53], v[100:101], v[0:1], v[54:55] op_sel_hi:[1,0,1]
	v_pk_mul_f32 v[118:119], v[52:53], v[112:113] op_sel_hi:[0,1]
	v_pk_fma_f32 v[118:119], v[52:53], v[114:115], v[118:119] op_sel:[1,0,0]
	v_pk_mul_f32 v[98:99], v[108:109], v[98:99] op_sel:[1,0]
	v_pk_fma_f32 v[54:55], v[52:53], v[96:97], v[98:99]
	v_add_f32_dpp v118, v118, v118 quad_perm:[1,0,3,2] row_mask:0xf bank_mask:0xf bound_ctrl:1
	v_add_f32_dpp v119, v119, v119 quad_perm:[1,0,3,2] row_mask:0xf bank_mask:0xf bound_ctrl:1
	s_nop 1
	ds_read_b128 v[112:115], v90 offset:0x7800
	v_add_f32_dpp v118, v118, v118 quad_perm:[2,3,0,1] row_mask:0xf bank_mask:0xf bound_ctrl:1
	s_nop 1
	ds_read_b128 v[96:99], v90 offset:0x3800
	v_add_f32_dpp v118, v118, v118 row_half_mirror row_mask:0xf bank_mask:0xf bound_ctrl:1
	s_nop 1
	ds_write2_b32 v93, v1, v119 offset0:0 offset1:36
	v_add_f32_dpp v2, v118, v118 row_mirror row_mask:0xf bank_mask:0xf bound_ctrl:1
	v_add_f32_dpp v118, v118, v118 row_mirror row_mask:0xf bank_mask:0xf bound_ctrl:1
	s_nop 0
	s_waitcnt lgkmcnt(4)
	v_permlane16_swap_b32_e32 v118, v2
	v_add_f32_e32 v118, v118, v2
	v_pk_fma_f32 v[52:53], v[102:103], v[118:119], v[54:55] op_sel_hi:[1,0,1]
	v_pk_mul_f32 v[0:1], v[52:53], v[120:121] op_sel_hi:[0,1]
	v_pk_fma_f32 v[0:1], v[52:53], v[122:123], v[0:1] op_sel:[1,0,0]
	v_pk_mul_f32 v[126:127], v[110:111], v[126:127] op_sel_hi:[0,1]
	v_pk_fma_f32 v[54:55], v[52:53], v[124:125], v[126:127]
	v_add_f32_dpp v0, v0, v0 quad_perm:[1,0,3,2] row_mask:0xf bank_mask:0xf bound_ctrl:1
	v_add_f32_dpp v1, v1, v1 quad_perm:[1,0,3,2] row_mask:0xf bank_mask:0xf bound_ctrl:1
	s_nop 1
	ds_read_b128 v[120:123], v90 offset:0x7a00
	v_add_f32_dpp v0, v0, v0 quad_perm:[2,3,0,1] row_mask:0xf bank_mask:0xf bound_ctrl:1
	s_nop 1
	ds_read_b128 v[124:127], v90 offset:0x3a00
	v_add_f32_dpp v0, v0, v0 row_half_mirror row_mask:0xf bank_mask:0xf bound_ctrl:1
	s_nop 1
	ds_read2st64_b32 v[108:109], v89 offset0:220 offset1:221
	ds_read2st64_b64 v[100:103], v88 offset0:92 offset1:93
	v_add_f32_dpp v2, v0, v0 row_mirror row_mask:0xf bank_mask:0xf bound_ctrl:1
	v_add_f32_dpp v0, v0, v0 row_mirror row_mask:0xf bank_mask:0xf bound_ctrl:1
	s_nop 0
	s_waitcnt lgkmcnt(7)
	v_permlane16_swap_b32_e32 v0, v2
	v_add_f32_e32 v0, v0, v2
	v_pk_fma_f32 v[52:53], v[104:105], v[0:1], v[54:55] op_sel_hi:[1,0,1]
	v_pk_mul_f32 v[118:119], v[52:53], v[4:5] op_sel_hi:[0,1]
	v_pk_fma_f32 v[118:119], v[52:53], v[6:7], v[118:119] op_sel:[1,0,0]
	v_pk_mul_f32 v[10:11], v[110:111], v[10:11] op_sel:[1,0]
	v_pk_fma_f32 v[54:55], v[52:53], v[8:9], v[10:11]
	v_add_f32_dpp v118, v118, v118 quad_perm:[1,0,3,2] row_mask:0xf bank_mask:0xf bound_ctrl:1
	v_add_f32_dpp v119, v119, v119 quad_perm:[1,0,3,2] row_mask:0xf bank_mask:0xf bound_ctrl:1
	s_nop 1
	ds_read_b128 v[4:7], v90 offset:0x7c00
	v_add_f32_dpp v118, v118, v118 quad_perm:[2,3,0,1] row_mask:0xf bank_mask:0xf bound_ctrl:1
	s_nop 1
	ds_read_b128 v[8:11], v90 offset:0x3c00
	v_add_f32_dpp v118, v118, v118 row_half_mirror row_mask:0xf bank_mask:0xf bound_ctrl:1
	s_nop 1
	ds_write2_b32 v93, v1, v119 offset0:72 offset1:108
	v_add_f32_dpp v2, v118, v118 row_mirror row_mask:0xf bank_mask:0xf bound_ctrl:1
	v_add_f32_dpp v118, v118, v118 row_mirror row_mask:0xf bank_mask:0xf bound_ctrl:1
	s_nop 0
	s_waitcnt lgkmcnt(4)
	v_permlane16_swap_b32_e32 v118, v2
	v_add_f32_e32 v118, v118, v2
	v_pk_fma_f32 v[52:53], v[106:107], v[118:119], v[54:55] op_sel_hi:[1,0,1]
	v_pk_mul_f32 v[0:1], v[52:53], v[112:113] op_sel_hi:[0,1]
	v_pk_fma_f32 v[0:1], v[52:53], v[114:115], v[0:1] op_sel:[1,0,0]
	v_pk_mul_f32 v[98:99], v[108:109], v[98:99] op_sel_hi:[0,1]
	v_pk_fma_f32 v[54:55], v[52:53], v[96:97], v[98:99]
	v_add_f32_dpp v0, v0, v0 quad_perm:[1,0,3,2] row_mask:0xf bank_mask:0xf bound_ctrl:1
	v_add_f32_dpp v1, v1, v1 quad_perm:[1,0,3,2] row_mask:0xf bank_mask:0xf bound_ctrl:1
	s_nop 1
	ds_read_b128 v[112:115], v90 offset:0x7e00
	v_add_f32_dpp v0, v0, v0 quad_perm:[2,3,0,1] row_mask:0xf bank_mask:0xf bound_ctrl:1
	s_nop 1
	ds_read_b128 v[96:99], v90 offset:0x3e00
	v_add_f32_dpp v0, v0, v0 row_half_mirror row_mask:0xf bank_mask:0xf bound_ctrl:1
	s_nop 1
	ds_read2st64_b32 v[110:111], v89 offset0:222 offset1:223
	ds_read2st64_b64 v[104:107], v88 offset0:94 offset1:95
	v_add_f32_dpp v2, v0, v0 row_mirror row_mask:0xf bank_mask:0xf bound_ctrl:1
	v_add_f32_dpp v0, v0, v0 row_mirror row_mask:0xf bank_mask:0xf bound_ctrl:1
	s_nop 0
	s_waitcnt lgkmcnt(7)
	v_permlane16_swap_b32_e32 v0, v2
	v_add_f32_e32 v0, v0, v2
	v_pk_fma_f32 v[52:53], v[100:101], v[0:1], v[54:55] op_sel_hi:[1,0,1]
	v_pk_mul_f32 v[118:119], v[52:53], v[120:121] op_sel_hi:[0,1]
	v_pk_fma_f32 v[118:119], v[52:53], v[122:123], v[118:119] op_sel:[1,0,0]
	v_pk_mul_f32 v[126:127], v[108:109], v[126:127] op_sel:[1,0]
	v_pk_fma_f32 v[54:55], v[52:53], v[124:125], v[126:127]
	v_add_f32_dpp v118, v118, v118 quad_perm:[1,0,3,2] row_mask:0xf bank_mask:0xf bound_ctrl:1
	v_add_f32_dpp v119, v119, v119 quad_perm:[1,0,3,2] row_mask:0xf bank_mask:0xf bound_ctrl:1
	s_nop 1
	s_nop 0
	v_add_f32_dpp v118, v118, v118 quad_perm:[2,3,0,1] row_mask:0xf bank_mask:0xf bound_ctrl:1
	s_nop 1
	s_nop 0
	v_add_f32_dpp v118, v118, v118 row_half_mirror row_mask:0xf bank_mask:0xf bound_ctrl:1
	s_nop 1
	ds_write2_b32 v93, v1, v119 offset0:144 offset1:180
	v_add_f32_dpp v2, v118, v118 row_mirror row_mask:0xf bank_mask:0xf bound_ctrl:1
	v_add_f32_dpp v118, v118, v118 row_mirror row_mask:0xf bank_mask:0xf bound_ctrl:1
	s_nop 0
	s_waitcnt lgkmcnt(2)
	v_permlane16_swap_b32_e32 v118, v2
	v_add_f32_e32 v118, v118, v2
	v_pk_fma_f32 v[52:53], v[102:103], v[118:119], v[54:55] op_sel_hi:[1,0,1]
	v_pk_mul_f32 v[0:1], v[52:53], v[4:5] op_sel_hi:[0,1]
	v_pk_fma_f32 v[0:1], v[52:53], v[6:7], v[0:1] op_sel:[1,0,0]
	v_pk_mul_f32 v[10:11], v[110:111], v[10:11] op_sel_hi:[0,1]
	v_pk_fma_f32 v[54:55], v[52:53], v[8:9], v[10:11]
	v_add_f32_dpp v0, v0, v0 quad_perm:[1,0,3,2] row_mask:0xf bank_mask:0xf bound_ctrl:1
	v_add_f32_dpp v1, v1, v1 quad_perm:[1,0,3,2] row_mask:0xf bank_mask:0xf bound_ctrl:1
	s_nop 1
	s_nop 0
	v_add_f32_dpp v0, v0, v0 quad_perm:[2,3,0,1] row_mask:0xf bank_mask:0xf bound_ctrl:1
	s_nop 1
	s_nop 0
	v_add_f32_dpp v0, v0, v0 row_half_mirror row_mask:0xf bank_mask:0xf bound_ctrl:1
	s_nop 1
	s_nop 0
	v_add_f32_dpp v2, v0, v0 row_mirror row_mask:0xf bank_mask:0xf bound_ctrl:1
	v_add_f32_dpp v0, v0, v0 row_mirror row_mask:0xf bank_mask:0xf bound_ctrl:1
	s_nop 0
	s_waitcnt lgkmcnt(1)
	v_permlane16_swap_b32_e32 v0, v2
	v_add_f32_e32 v0, v0, v2
	v_pk_fma_f32 v[52:53], v[104:105], v[0:1], v[54:55] op_sel_hi:[1,0,1]
	v_pk_mul_f32 v[118:119], v[52:53], v[112:113] op_sel_hi:[0,1]
	v_pk_fma_f32 v[118:119], v[52:53], v[114:115], v[118:119] op_sel:[1,0,0]
	v_pk_mul_f32 v[98:99], v[110:111], v[98:99] op_sel:[1,0]
	v_pk_fma_f32 v[54:55], v[52:53], v[96:97], v[98:99]
	v_add_f32_dpp v118, v118, v118 quad_perm:[1,0,3,2] row_mask:0xf bank_mask:0xf bound_ctrl:1
	v_add_f32_dpp v119, v119, v119 quad_perm:[1,0,3,2] row_mask:0xf bank_mask:0xf bound_ctrl:1
	s_nop 1
	s_nop 0
	v_add_f32_dpp v118, v118, v118 quad_perm:[2,3,0,1] row_mask:0xf bank_mask:0xf bound_ctrl:1
	s_nop 1
	s_nop 0
	v_add_f32_dpp v118, v118, v118 row_half_mirror row_mask:0xf bank_mask:0xf bound_ctrl:1
	s_nop 1
	ds_write2_b32 v93, v1, v119 offset0:216 offset1:252
	v_add_f32_dpp v2, v118, v118 row_mirror row_mask:0xf bank_mask:0xf bound_ctrl:1
	v_add_f32_dpp v118, v118, v118 row_mirror row_mask:0xf bank_mask:0xf bound_ctrl:1
	s_nop 0
	s_nop 0
	v_permlane16_swap_b32_e32 v118, v2
	v_add_f32_e32 v118, v118, v2
	v_pk_fma_f32 v[52:53], v[106:107], v[118:119], v[54:55] op_sel_hi:[1,0,1]
